# v082 + non-temporal cache hint on the streaming epilogue traffic (FFN-in / W_in output stores and the FFN1-out f32 residual loads) to keep GEMM operand tiles resident in L2
# baseline (speedup 1.0000x reference)
; __device__ __forceinline__ unsigned pk2(float lo, float hi) { f32x2 v = {lo, hi}; bf16x2_t b = __builtin_convertvector(v, bf16x2_t); return __builtin_bit_cast(unsigned, b); }
; __device__ __forceinline__ float sigmoidf_(float x) { return __builtin_amdgcn_rcpf(1.0f + __builtin_amdgcn_exp2f(-x * LOG2E)); }
;     __device__ __forceinline__ void operator()(const f32x4 (&acc)[2][2][4][2], const Unit& u, int wr, int wc, int fr, int fq, LAS unsigned char* lds, int tid) const {
;     ...
;             for (int m = 0; m < 4; ++m) { const size_t row = (size_t)(row0 + ai * HALF + m * 16); const float rs = rsv[ai][m]; gbf16* rowp = O + row * FF + col0;
;                 float h[8];
; #pragma unroll
;                 for (int n = 0; n < 2; ++n)
; #pragma unroll
;                     for (int e = 0; e < 4; ++e) { const float g = acc[ai][0][m][n][e] * rs, uu = acc[ai][1][m][n][e] * rs; h[n * 4 + e] = g * sigmoidf_(g) * uu; }
;                 u32x4 w; w.x = pk2(h[0], h[1]); w.y = pk2(h[2], h[3]); w.z = pk2(h[4], h[5]); w.w = pk2(h[6], h[7]);
;                 *(gu32x4*)rowp = w; }
.Lk8_rs_hit:
	s_andn2_b64 vcc, exec, s[2:3]
	v_lshl_or_b32 v174, s1, 7, v151
	v_mov_b32_e32 v170, v226
	v_mov_b32_e32 v166, v236
	v_mov_b32_e32 v162, v237
	v_mov_b32_e32 v158, v244
	v_mov_b32_e32 v154, v245
	v_mov_b32_e32 v150, v246
	v_mov_b32_e32 v144, v247
	v_mov_b32_e32 v142, v248
	v_pk_mul_f32 v[126:127], v[126:127], v[170:171] op_sel_hi:[1,0]
	v_mul_f32_e32 v141, 0xbfb8aa3b, v126
	v_exp_f32_e32 v141, v141
	v_pk_mul_f32 v[122:123], v[122:123], v[170:171] op_sel_hi:[1,0]
	v_pk_mul_f32 v[124:125], v[124:125], v[170:171] op_sel_hi:[1,0]
	v_pk_mul_f32 v[118:119], v[118:119], v[170:171] op_sel_hi:[1,0]
	v_add_f32_e32 v141, 1.0, v141
	v_rcp_f32_e32 v176, v141
	v_mul_f32_e32 v141, 0xbfb8aa3b, v127
	v_exp_f32_e32 v141, v141
	v_pk_mul_f32 v[114:115], v[114:115], v[170:171] op_sel_hi:[1,0]
	v_ashrrev_i32_e32 v175, 31, v174
	v_mov_b64_e32 v[148:149], s[88:89]
	v_add_f32_e32 v141, 1.0, v141
	v_rcp_f32_e32 v177, v141
	v_pk_mul_f32 v[116:117], v[116:117], v[170:171] op_sel_hi:[1,0]
	v_mad_i64_i32 v[172:173], s[0:1], v172, s79, v[148:149]
	v_pk_mul_f32 v[126:127], v[126:127], v[176:177]
	v_pk_mul_f32 v[110:111], v[110:111], v[166:167] op_sel_hi:[1,0]
	v_pk_mul_f32 v[122:123], v[122:123], v[126:127]
	v_pk_mul_f32 v[126:127], v[128:129], v[170:171] op_sel_hi:[1,0]
	v_pk_mul_f32 v[106:107], v[106:107], v[166:167] op_sel_hi:[1,0]
	v_mul_f32_e32 v128, 0xbfb8aa3b, v126
	v_mul_f32_e32 v129, 0xbfb8aa3b, v127
	v_exp_f32_e32 v128, v128
	v_exp_f32_e32 v129, v129
	v_pk_mul_f32 v[108:109], v[108:109], v[166:167] op_sel_hi:[1,0]
	v_pk_mul_f32 v[102:103], v[102:103], v[166:167] op_sel_hi:[1,0]
	v_add_f32_e32 v128, 1.0, v128
	v_add_f32_e32 v129, 1.0, v129
	v_rcp_f32_e32 v128, v128
	v_rcp_f32_e32 v129, v129
	v_pk_mul_f32 v[98:99], v[98:99], v[166:167] op_sel_hi:[1,0]
	v_pk_mul_f32 v[100:101], v[100:101], v[166:167] op_sel_hi:[1,0]
	v_pk_mul_f32 v[94:95], v[94:95], v[162:163] op_sel_hi:[1,0]
	v_pk_mul_f32 v[126:127], v[126:127], v[128:129]
	v_pk_mul_f32 v[90:91], v[90:91], v[162:163] op_sel_hi:[1,0]
	v_pk_mul_f32 v[124:125], v[124:125], v[126:127]
	v_mul_f32_e32 v126, 0xbfb8aa3b, v118
	v_mul_f32_e32 v127, 0xbfb8aa3b, v119
	v_exp_f32_e32 v126, v126
	v_exp_f32_e32 v127, v127
	v_pk_mul_f32 v[92:93], v[92:93], v[162:163] op_sel_hi:[1,0]
	v_pk_mul_f32 v[86:87], v[86:87], v[162:163] op_sel_hi:[1,0]
	v_add_f32_e32 v126, 1.0, v126
	v_add_f32_e32 v127, 1.0, v127
	v_rcp_f32_e32 v126, v126
	v_rcp_f32_e32 v127, v127
	v_pk_mul_f32 v[82:83], v[82:83], v[162:163] op_sel_hi:[1,0]
	v_pk_mul_f32 v[84:85], v[84:85], v[162:163] op_sel_hi:[1,0]
	v_pk_mul_f32 v[78:79], v[78:79], v[158:159] op_sel_hi:[1,0]
	v_pk_mul_f32 v[118:119], v[118:119], v[126:127]
	v_pk_mul_f32 v[74:75], v[74:75], v[158:159] op_sel_hi:[1,0]
	v_pk_mul_f32 v[118:119], v[114:115], v[118:119]
	v_pk_mul_f32 v[114:115], v[120:121], v[170:171] op_sel_hi:[1,0]
	v_cvt_pk_bf16_f32 v118, v118, v119
	v_mul_f32_e32 v120, 0xbfb8aa3b, v114
	v_mul_f32_e32 v121, 0xbfb8aa3b, v115
	v_exp_f32_e32 v120, v120
	v_exp_f32_e32 v121, v121
	v_pk_mul_f32 v[76:77], v[76:77], v[158:159] op_sel_hi:[1,0]
	v_pk_mul_f32 v[70:71], v[70:71], v[158:159] op_sel_hi:[1,0]
	v_add_f32_e32 v120, 1.0, v120
	v_add_f32_e32 v121, 1.0, v121
	v_rcp_f32_e32 v120, v120
	v_rcp_f32_e32 v121, v121
	v_pk_mul_f32 v[66:67], v[66:67], v[158:159] op_sel_hi:[1,0]
	v_pk_mul_f32 v[68:69], v[68:69], v[158:159] op_sel_hi:[1,0]
	v_pk_mul_f32 v[62:63], v[62:63], v[154:155] op_sel_hi:[1,0]
	v_pk_mul_f32 v[114:115], v[114:115], v[120:121]
	v_pk_mul_f32 v[58:59], v[58:59], v[154:155] op_sel_hi:[1,0]
	v_pk_mul_f32 v[120:121], v[116:117], v[114:115]
	v_lshlrev_b64 v[114:115], 1, v[174:175]
	v_lshl_add_u64 v[126:127], v[172:173], 0, v[114:115]
	v_cvt_pk_bf16_f32 v116, v122, v123
	v_cvt_pk_bf16_f32 v117, v124, v125
	v_cvt_pk_bf16_f32 v119, v120, v121
	global_store_dwordx4 v[126:127], v[116:119], off nt
	v_pk_mul_f32 v[60:61], v[60:61], v[154:155] op_sel_hi:[1,0]
	v_pk_mul_f32 v[54:55], v[54:55], v[154:155] op_sel_hi:[1,0]
	v_mul_f32_e32 v118, 0xbfb8aa3b, v110
	v_mul_f32_e32 v119, 0xbfb8aa3b, v111
	v_exp_f32_e32 v118, v118
	v_exp_f32_e32 v119, v119
	v_mad_i64_i32 v[116:117], s[0:1], v168, s79, v[148:149]
	v_add_f32_e32 v118, 1.0, v118
	v_add_f32_e32 v119, 1.0, v119
	v_rcp_f32_e32 v118, v118
	v_rcp_f32_e32 v119, v119
	v_pk_mul_f32 v[50:51], v[50:51], v[154:155] op_sel_hi:[1,0]
	v_pk_mul_f32 v[52:53], v[52:53], v[154:155] op_sel_hi:[1,0]
	v_pk_mul_f32 v[46:47], v[46:47], v[150:151] op_sel_hi:[1,0]
	v_pk_mul_f32 v[110:111], v[110:111], v[118:119]
	v_pk_mul_f32 v[42:43], v[42:43], v[150:151] op_sel_hi:[1,0]
	v_pk_mul_f32 v[106:107], v[106:107], v[110:111]
	v_pk_mul_f32 v[110:111], v[112:113], v[166:167] op_sel_hi:[1,0]
	v_pk_mul_f32 v[44:45], v[44:45], v[150:151] op_sel_hi:[1,0]
	v_mul_f32_e32 v112, 0xbfb8aa3b, v110
	v_mul_f32_e32 v113, 0xbfb8aa3b, v111
	v_exp_f32_e32 v112, v112
	v_exp_f32_e32 v113, v113
	v_pk_mul_f32 v[38:39], v[38:39], v[150:151] op_sel_hi:[1,0]
	v_pk_mul_f32 v[34:35], v[34:35], v[150:151] op_sel_hi:[1,0]
	v_add_f32_e32 v112, 1.0, v112
	v_add_f32_e32 v113, 1.0, v113
	v_rcp_f32_e32 v112, v112
	v_rcp_f32_e32 v113, v113
	v_pk_mul_f32 v[36:37], v[36:37], v[150:151] op_sel_hi:[1,0]
	v_pk_mul_f32 v[30:31], v[30:31], v[144:145] op_sel_hi:[1,0]
	v_pk_mul_f32 v[26:27], v[26:27], v[144:145] op_sel_hi:[1,0]
	v_pk_mul_f32 v[110:111], v[110:111], v[112:113]
	v_pk_mul_f32 v[28:29], v[28:29], v[144:145] op_sel_hi:[1,0]
	v_pk_mul_f32 v[108:109], v[108:109], v[110:111]
	v_mul_f32_e32 v110, 0xbfb8aa3b, v102
	v_mul_f32_e32 v111, 0xbfb8aa3b, v103
	v_exp_f32_e32 v110, v110
	v_exp_f32_e32 v111, v111
	v_pk_mul_f32 v[22:23], v[22:23], v[144:145] op_sel_hi:[1,0]
	v_pk_mul_f32 v[18:19], v[18:19], v[144:145] op_sel_hi:[1,0]
; __device__ __forceinline__ unsigned pk2(float lo, float hi) { f32x2 v = {lo, hi}; bf16x2_t b = __builtin_convertvector(v, bf16x2_t); return __builtin_bit_cast(unsigned, b); }
; __device__ __forceinline__ float sigmoidf_(float x) { return __builtin_amdgcn_rcpf(1.0f + __builtin_amdgcn_exp2f(-x * LOG2E)); }
;     __device__ __forceinline__ void operator()(const f32x4 (&acc)[2][2][4][2], const Unit& u, int wr, int wc, int fr, int fq, LAS unsigned char* lds, int tid) const {
;     ...
;             for (int m = 0; m < 4; ++m) { const size_t row = (size_t)(row0 + ai * HALF + m * 16); const float rs = rsv[ai][m]; gbf16* rowp = O + row * FF + col0;
;                 float h[8];
; #pragma unroll
;                 for (int n = 0; n < 2; ++n)
; #pragma unroll
;                     for (int e = 0; e < 4; ++e) { const float g = acc[ai][0][m][n][e] * rs, uu = acc[ai][1][m][n][e] * rs; h[n * 4 + e] = g * sigmoidf_(g) * uu; }
;                 u32x4 w; w.x = pk2(h[0], h[1]); w.y = pk2(h[2], h[3]); w.z = pk2(h[4], h[5]); w.w = pk2(h[6], h[7]);
;                 *(gu32x4*)rowp = w; }
	v_add_f32_e32 v110, 1.0, v110
	v_add_f32_e32 v111, 1.0, v111
	v_rcp_f32_e32 v110, v110
	v_rcp_f32_e32 v111, v111
	v_pk_mul_f32 v[20:21], v[20:21], v[144:145] op_sel_hi:[1,0]
	v_pk_mul_f32 v[14:15], v[14:15], v[142:143] op_sel_hi:[1,0]
	v_pk_mul_f32 v[10:11], v[10:11], v[142:143] op_sel_hi:[1,0]
	v_pk_mul_f32 v[102:103], v[102:103], v[110:111]
	v_lshl_add_u64 v[110:111], v[116:117], 0, v[114:115]
	v_pk_mul_f32 v[102:103], v[98:99], v[102:103]
	v_pk_mul_f32 v[98:99], v[104:105], v[166:167] op_sel_hi:[1,0]
	v_pk_mul_f32 v[12:13], v[12:13], v[142:143] op_sel_hi:[1,0]
	v_mul_f32_e32 v104, 0xbfb8aa3b, v98
	v_mul_f32_e32 v105, 0xbfb8aa3b, v99
	v_exp_f32_e32 v104, v104
	v_exp_f32_e32 v105, v105
	v_pk_mul_f32 v[6:7], v[6:7], v[142:143] op_sel_hi:[1,0]
	v_pk_mul_f32 v[2:3], v[2:3], v[142:143] op_sel_hi:[1,0]
	v_add_f32_e32 v104, 1.0, v104
	v_add_f32_e32 v105, 1.0, v105
	v_rcp_f32_e32 v104, v104
	v_rcp_f32_e32 v105, v105
	v_pk_mul_f32 v[4:5], v[4:5], v[142:143] op_sel_hi:[1,0]
	v_pk_mul_f32 v[98:99], v[98:99], v[104:105]
	s_nop 0
	v_pk_mul_f32 v[104:105], v[100:101], v[98:99]
	v_cvt_pk_bf16_f32 v98, v106, v107
	v_cvt_pk_bf16_f32 v99, v108, v109
	v_cvt_pk_bf16_f32 v100, v102, v103
	v_cvt_pk_bf16_f32 v101, v104, v105
	global_store_dwordx4 v[110:111], v[98:101], off nt
	s_nop 1
	v_mul_f32_e32 v100, 0xbfb8aa3b, v94
	v_mul_f32_e32 v101, 0xbfb8aa3b, v95
	v_exp_f32_e32 v100, v100
	v_exp_f32_e32 v101, v101
	v_mad_i64_i32 v[98:99], s[0:1], v164, s79, v[148:149]
	v_add_f32_e32 v100, 1.0, v100
	v_add_f32_e32 v101, 1.0, v101
	v_rcp_f32_e32 v100, v100
	v_rcp_f32_e32 v101, v101
	s_nop 0
	v_pk_mul_f32 v[94:95], v[94:95], v[100:101]
	s_nop 0
	v_pk_mul_f32 v[90:91], v[90:91], v[94:95]
	v_pk_mul_f32 v[94:95], v[96:97], v[162:163] op_sel_hi:[1,0]
	s_nop 0
	v_mul_f32_e32 v96, 0xbfb8aa3b, v94
	v_mul_f32_e32 v97, 0xbfb8aa3b, v95
	v_exp_f32_e32 v96, v96
	v_exp_f32_e32 v97, v97
	v_add_f32_e32 v96, 1.0, v96
	v_add_f32_e32 v97, 1.0, v97
	v_rcp_f32_e32 v96, v96
	v_rcp_f32_e32 v97, v97
	s_nop 0
	v_pk_mul_f32 v[94:95], v[94:95], v[96:97]
	s_nop 0
	v_pk_mul_f32 v[92:93], v[92:93], v[94:95]
	v_mul_f32_e32 v94, 0xbfb8aa3b, v86
	v_mul_f32_e32 v95, 0xbfb8aa3b, v87
	v_exp_f32_e32 v94, v94
	v_exp_f32_e32 v95, v95
	v_add_f32_e32 v94, 1.0, v94
	v_add_f32_e32 v95, 1.0, v95
	v_rcp_f32_e32 v94, v94
	v_rcp_f32_e32 v95, v95
	s_nop 0
	v_pk_mul_f32 v[86:87], v[86:87], v[94:95]
	s_nop 0
	v_pk_mul_f32 v[86:87], v[82:83], v[86:87]
	v_pk_mul_f32 v[82:83], v[88:89], v[162:163] op_sel_hi:[1,0]
	v_lshl_add_u64 v[94:95], v[98:99], 0, v[114:115]
	v_mul_f32_e32 v88, 0xbfb8aa3b, v82
	v_mul_f32_e32 v89, 0xbfb8aa3b, v83
	v_exp_f32_e32 v88, v88
	v_exp_f32_e32 v89, v89
	v_add_f32_e32 v88, 1.0, v88
	v_add_f32_e32 v89, 1.0, v89
	v_rcp_f32_e32 v88, v88
	v_rcp_f32_e32 v89, v89
	s_nop 0
	v_pk_mul_f32 v[82:83], v[82:83], v[88:89]
	s_nop 0
	v_pk_mul_f32 v[88:89], v[84:85], v[82:83]
	v_cvt_pk_bf16_f32 v82, v90, v91
	v_cvt_pk_bf16_f32 v83, v92, v93
	v_cvt_pk_bf16_f32 v84, v86, v87
	v_cvt_pk_bf16_f32 v85, v88, v89
	global_store_dwordx4 v[94:95], v[82:85], off nt
	s_nop 1
	v_mul_f32_e32 v84, 0xbfb8aa3b, v78
	v_mul_f32_e32 v85, 0xbfb8aa3b, v79
	v_exp_f32_e32 v84, v84
	v_exp_f32_e32 v85, v85
	v_mad_i64_i32 v[82:83], s[0:1], v160, s79, v[148:149]
	v_add_f32_e32 v84, 1.0, v84
	v_add_f32_e32 v85, 1.0, v85
	v_rcp_f32_e32 v84, v84
	v_rcp_f32_e32 v85, v85
	s_nop 0
	v_pk_mul_f32 v[78:79], v[78:79], v[84:85]
	s_nop 0
	v_pk_mul_f32 v[74:75], v[74:75], v[78:79]
	v_pk_mul_f32 v[78:79], v[80:81], v[158:159] op_sel_hi:[1,0]
	s_nop 0
	v_mul_f32_e32 v80, 0xbfb8aa3b, v78
	v_mul_f32_e32 v81, 0xbfb8aa3b, v79
	v_exp_f32_e32 v80, v80
	v_exp_f32_e32 v81, v81
	v_add_f32_e32 v80, 1.0, v80
	v_add_f32_e32 v81, 1.0, v81
	v_rcp_f32_e32 v80, v80
	v_rcp_f32_e32 v81, v81
	s_nop 0
	v_pk_mul_f32 v[78:79], v[78:79], v[80:81]
	s_nop 0
	v_pk_mul_f32 v[76:77], v[76:77], v[78:79]
	v_mul_f32_e32 v78, 0xbfb8aa3b, v70
	v_mul_f32_e32 v79, 0xbfb8aa3b, v71
	v_exp_f32_e32 v78, v78
	v_exp_f32_e32 v79, v79
	v_add_f32_e32 v78, 1.0, v78
	v_add_f32_e32 v79, 1.0, v79
	v_rcp_f32_e32 v78, v78
	v_rcp_f32_e32 v79, v79
	s_nop 0
	v_pk_mul_f32 v[70:71], v[70:71], v[78:79]
	s_nop 0
	v_pk_mul_f32 v[70:71], v[66:67], v[70:71]
	v_pk_mul_f32 v[66:67], v[72:73], v[158:159] op_sel_hi:[1,0]
	v_lshl_add_u64 v[78:79], v[82:83], 0, v[114:115]
	v_mul_f32_e32 v72, 0xbfb8aa3b, v66
	v_mul_f32_e32 v73, 0xbfb8aa3b, v67
	v_exp_f32_e32 v72, v72
	v_exp_f32_e32 v73, v73
	v_add_f32_e32 v72, 1.0, v72
	v_add_f32_e32 v73, 1.0, v73
	v_rcp_f32_e32 v72, v72
	v_rcp_f32_e32 v73, v73
	s_nop 0
	v_pk_mul_f32 v[66:67], v[66:67], v[72:73]
	s_nop 0
	v_pk_mul_f32 v[72:73], v[68:69], v[66:67]
	v_cvt_pk_bf16_f32 v66, v74, v75
	v_cvt_pk_bf16_f32 v67, v76, v77
	v_cvt_pk_bf16_f32 v68, v70, v71
	v_cvt_pk_bf16_f32 v69, v72, v73
	global_store_dwordx4 v[78:79], v[66:69], off nt
	s_nop 1
	v_mul_f32_e32 v68, 0xbfb8aa3b, v62
	v_mul_f32_e32 v69, 0xbfb8aa3b, v63
	v_exp_f32_e32 v68, v68
	v_exp_f32_e32 v69, v69
	v_mad_i64_i32 v[66:67], s[0:1], v156, s79, v[148:149]
	v_add_f32_e32 v68, 1.0, v68
	v_add_f32_e32 v69, 1.0, v69
	v_rcp_f32_e32 v68, v68
	v_rcp_f32_e32 v69, v69
	s_nop 0
	v_pk_mul_f32 v[62:63], v[62:63], v[68:69]
	s_nop 0
	v_pk_mul_f32 v[58:59], v[58:59], v[62:63]
	v_pk_mul_f32 v[62:63], v[64:65], v[154:155] op_sel_hi:[1,0]
	s_nop 0
	v_mul_f32_e32 v64, 0xbfb8aa3b, v62
	v_mul_f32_e32 v65, 0xbfb8aa3b, v63
	v_exp_f32_e32 v64, v64
	v_exp_f32_e32 v65, v65
	v_add_f32_e32 v64, 1.0, v64
	v_add_f32_e32 v65, 1.0, v65
	v_rcp_f32_e32 v64, v64
	v_rcp_f32_e32 v65, v65
	s_nop 0
	v_pk_mul_f32 v[62:63], v[62:63], v[64:65]
	s_nop 0
	v_pk_mul_f32 v[60:61], v[60:61], v[62:63]
	v_mul_f32_e32 v62, 0xbfb8aa3b, v54
	v_mul_f32_e32 v63, 0xbfb8aa3b, v55
; __device__ __forceinline__ unsigned pk2(float lo, float hi) { f32x2 v = {lo, hi}; bf16x2_t b = __builtin_convertvector(v, bf16x2_t); return __builtin_bit_cast(unsigned, b); }
; __device__ __forceinline__ float sigmoidf_(float x) { return __builtin_amdgcn_rcpf(1.0f + __builtin_amdgcn_exp2f(-x * LOG2E)); }
; #define PG8_BAR __builtin_amdgcn_s_barrier()
;     __device__ __forceinline__ void operator()(const f32x4 (&acc)[2][2][4][2], const Unit& u, int wr, int wc, int fr, int fq, LAS unsigned char* lds, int tid) const {
;     ...
;             for (int m = 0; m < 4; ++m) { const size_t row = (size_t)(row0 + ai * HALF + m * 16); const float rs = rsv[ai][m]; gbf16* rowp = O + row * FF + col0;
;                 float h[8];
; #pragma unroll
;                 for (int n = 0; n < 2; ++n)
; #pragma unroll
;                     for (int e = 0; e < 4; ++e) { const float g = acc[ai][0][m][n][e] * rs, uu = acc[ai][1][m][n][e] * rs; h[n * 4 + e] = g * sigmoidf_(g) * uu; }
;                 u32x4 w; w.x = pk2(h[0], h[1]); w.y = pk2(h[2], h[3]); w.z = pk2(h[4], h[5]); w.w = pk2(h[6], h[7]);
;                 *(gu32x4*)rowp = w; }
; template <class Epi, class Sched>
; __device__ __forceinline__ void gemm_phase(LAS unsigned char* lds, const int tid, const Gemm g, const Sched& S, const Epi& E) {
;     ...
;         if (wr == 1) PG8_BAR;
	v_exp_f32_e32 v62, v62
	v_exp_f32_e32 v63, v63
	v_add_f32_e32 v62, 1.0, v62
	v_add_f32_e32 v63, 1.0, v63
	v_rcp_f32_e32 v62, v62
	v_rcp_f32_e32 v63, v63
	s_nop 0
	v_pk_mul_f32 v[54:55], v[54:55], v[62:63]
	s_nop 0
	v_pk_mul_f32 v[54:55], v[50:51], v[54:55]
	v_pk_mul_f32 v[50:51], v[56:57], v[154:155] op_sel_hi:[1,0]
	v_lshl_add_u64 v[62:63], v[66:67], 0, v[114:115]
	v_mul_f32_e32 v56, 0xbfb8aa3b, v50
	v_mul_f32_e32 v57, 0xbfb8aa3b, v51
	v_exp_f32_e32 v56, v56
	v_exp_f32_e32 v57, v57
	v_add_f32_e32 v56, 1.0, v56
	v_add_f32_e32 v57, 1.0, v57
	v_rcp_f32_e32 v56, v56
	v_rcp_f32_e32 v57, v57
	s_nop 0
	v_pk_mul_f32 v[50:51], v[50:51], v[56:57]
	s_nop 0
	v_pk_mul_f32 v[56:57], v[52:53], v[50:51]
	v_cvt_pk_bf16_f32 v50, v58, v59
	v_cvt_pk_bf16_f32 v51, v60, v61
	v_cvt_pk_bf16_f32 v52, v54, v55
	v_cvt_pk_bf16_f32 v53, v56, v57
	global_store_dwordx4 v[62:63], v[50:53], off nt
	s_nop 1
	v_mul_f32_e32 v52, 0xbfb8aa3b, v46
	v_mul_f32_e32 v53, 0xbfb8aa3b, v47
	v_exp_f32_e32 v52, v52
	v_exp_f32_e32 v53, v53
	v_mad_i64_i32 v[50:51], s[0:1], v152, s79, v[148:149]
	v_add_f32_e32 v52, 1.0, v52
	v_add_f32_e32 v53, 1.0, v53
	v_rcp_f32_e32 v52, v52
	v_rcp_f32_e32 v53, v53
	s_nop 0
	v_pk_mul_f32 v[46:47], v[46:47], v[52:53]
	s_nop 0
	v_pk_mul_f32 v[42:43], v[42:43], v[46:47]
	v_pk_mul_f32 v[46:47], v[48:49], v[150:151] op_sel_hi:[1,0]
	s_nop 0
	v_mul_f32_e32 v48, 0xbfb8aa3b, v46
	v_mul_f32_e32 v49, 0xbfb8aa3b, v47
	v_exp_f32_e32 v48, v48
	v_exp_f32_e32 v49, v49
	v_add_f32_e32 v48, 1.0, v48
	v_add_f32_e32 v49, 1.0, v49
	v_rcp_f32_e32 v48, v48
	v_rcp_f32_e32 v49, v49
	s_nop 0
	v_pk_mul_f32 v[46:47], v[46:47], v[48:49]
	s_nop 0
	v_pk_mul_f32 v[44:45], v[44:45], v[46:47]
	v_mul_f32_e32 v46, 0xbfb8aa3b, v38
	v_mul_f32_e32 v47, 0xbfb8aa3b, v39
	v_exp_f32_e32 v46, v46
	v_exp_f32_e32 v47, v47
	v_add_f32_e32 v46, 1.0, v46
	v_add_f32_e32 v47, 1.0, v47
	v_rcp_f32_e32 v46, v46
	v_rcp_f32_e32 v47, v47
	s_nop 0
	v_pk_mul_f32 v[38:39], v[38:39], v[46:47]
	s_nop 0
	v_pk_mul_f32 v[38:39], v[34:35], v[38:39]
	v_pk_mul_f32 v[34:35], v[40:41], v[150:151] op_sel_hi:[1,0]
	v_lshl_add_u64 v[46:47], v[50:51], 0, v[114:115]
	v_mul_f32_e32 v40, 0xbfb8aa3b, v34
	v_mul_f32_e32 v41, 0xbfb8aa3b, v35
	v_exp_f32_e32 v40, v40
	v_exp_f32_e32 v41, v41
	v_add_f32_e32 v40, 1.0, v40
	v_add_f32_e32 v41, 1.0, v41
	v_rcp_f32_e32 v40, v40
	v_rcp_f32_e32 v41, v41
	s_nop 0
	v_pk_mul_f32 v[34:35], v[34:35], v[40:41]
	s_nop 0
	v_pk_mul_f32 v[40:41], v[36:37], v[34:35]
	v_cvt_pk_bf16_f32 v34, v42, v43
	v_cvt_pk_bf16_f32 v35, v44, v45
	v_cvt_pk_bf16_f32 v36, v38, v39
	v_cvt_pk_bf16_f32 v37, v40, v41
	global_store_dwordx4 v[46:47], v[34:37], off nt
	s_nop 1
	v_mul_f32_e32 v36, 0xbfb8aa3b, v30
	v_mul_f32_e32 v37, 0xbfb8aa3b, v31
	v_exp_f32_e32 v36, v36
	v_exp_f32_e32 v37, v37
	v_mad_i64_i32 v[34:35], s[0:1], v146, s79, v[148:149]
	v_add_f32_e32 v36, 1.0, v36
	v_add_f32_e32 v37, 1.0, v37
	v_rcp_f32_e32 v36, v36
	v_rcp_f32_e32 v37, v37
	s_nop 0
	v_pk_mul_f32 v[30:31], v[30:31], v[36:37]
	s_nop 0
	v_pk_mul_f32 v[26:27], v[26:27], v[30:31]
	v_pk_mul_f32 v[30:31], v[32:33], v[144:145] op_sel_hi:[1,0]
	s_nop 0
	v_mul_f32_e32 v32, 0xbfb8aa3b, v30
	v_mul_f32_e32 v33, 0xbfb8aa3b, v31
	v_exp_f32_e32 v32, v32
	v_exp_f32_e32 v33, v33
	v_add_f32_e32 v32, 1.0, v32
	v_add_f32_e32 v33, 1.0, v33
	v_rcp_f32_e32 v32, v32
	v_rcp_f32_e32 v33, v33
	s_nop 0
	v_pk_mul_f32 v[30:31], v[30:31], v[32:33]
	s_nop 0
	v_pk_mul_f32 v[28:29], v[28:29], v[30:31]
	v_mul_f32_e32 v30, 0xbfb8aa3b, v22
	v_mul_f32_e32 v31, 0xbfb8aa3b, v23
	v_exp_f32_e32 v30, v30
	v_exp_f32_e32 v31, v31
	v_add_f32_e32 v30, 1.0, v30
	v_add_f32_e32 v31, 1.0, v31
	v_rcp_f32_e32 v30, v30
	v_rcp_f32_e32 v31, v31
	s_nop 0
	v_pk_mul_f32 v[22:23], v[22:23], v[30:31]
	s_nop 0
	v_pk_mul_f32 v[22:23], v[18:19], v[22:23]
	v_pk_mul_f32 v[18:19], v[24:25], v[144:145] op_sel_hi:[1,0]
	v_lshl_add_u64 v[30:31], v[34:35], 0, v[114:115]
	v_mul_f32_e32 v24, 0xbfb8aa3b, v18
	v_mul_f32_e32 v25, 0xbfb8aa3b, v19
	v_exp_f32_e32 v24, v24
	v_exp_f32_e32 v25, v25
	v_add_f32_e32 v24, 1.0, v24
	v_add_f32_e32 v25, 1.0, v25
	v_rcp_f32_e32 v24, v24
	v_rcp_f32_e32 v25, v25
	s_nop 0
	v_pk_mul_f32 v[18:19], v[18:19], v[24:25]
	s_nop 0
	v_pk_mul_f32 v[24:25], v[20:21], v[18:19]
	v_cvt_pk_bf16_f32 v18, v26, v27
	v_cvt_pk_bf16_f32 v19, v28, v29
	v_cvt_pk_bf16_f32 v20, v22, v23
	v_cvt_pk_bf16_f32 v21, v24, v25
	global_store_dwordx4 v[30:31], v[18:21], off nt
	s_nop 1
	v_mul_f32_e32 v20, 0xbfb8aa3b, v14
	v_mul_f32_e32 v21, 0xbfb8aa3b, v15
	v_exp_f32_e32 v20, v20
	v_exp_f32_e32 v21, v21
	v_mad_i64_i32 v[18:19], s[0:1], v140, s79, v[148:149]
	v_add_f32_e32 v20, 1.0, v20
	v_add_f32_e32 v21, 1.0, v21
	v_rcp_f32_e32 v20, v20
	v_rcp_f32_e32 v21, v21
	s_mov_b64 s[0:1], -1
	v_pk_mul_f32 v[14:15], v[14:15], v[20:21]
	s_nop 0
	v_pk_mul_f32 v[10:11], v[10:11], v[14:15]
	v_pk_mul_f32 v[14:15], v[16:17], v[142:143] op_sel_hi:[1,0]
	s_nop 0
	v_mul_f32_e32 v16, 0xbfb8aa3b, v14
	v_mul_f32_e32 v17, 0xbfb8aa3b, v15
	v_exp_f32_e32 v16, v16
	v_exp_f32_e32 v17, v17
	v_add_f32_e32 v16, 1.0, v16
	v_add_f32_e32 v17, 1.0, v17
	v_rcp_f32_e32 v16, v16
	v_rcp_f32_e32 v17, v17
	s_nop 0
	v_pk_mul_f32 v[14:15], v[14:15], v[16:17]
	s_nop 0
	v_pk_mul_f32 v[12:13], v[12:13], v[14:15]
	v_mul_f32_e32 v14, 0xbfb8aa3b, v6
	v_mul_f32_e32 v15, 0xbfb8aa3b, v7
	v_exp_f32_e32 v14, v14
	v_exp_f32_e32 v15, v15
	v_add_f32_e32 v14, 1.0, v14
	v_add_f32_e32 v15, 1.0, v15
	v_rcp_f32_e32 v14, v14
	v_rcp_f32_e32 v15, v15
	s_nop 0
	v_pk_mul_f32 v[6:7], v[6:7], v[14:15]
	s_nop 0
	v_pk_mul_f32 v[6:7], v[2:3], v[6:7]
	v_pk_mul_f32 v[2:3], v[8:9], v[142:143] op_sel_hi:[1,0]
	v_lshl_add_u64 v[14:15], v[18:19], 0, v[114:115]
	v_mul_f32_e32 v8, 0xbfb8aa3b, v2
	v_mul_f32_e32 v9, 0xbfb8aa3b, v3
	v_exp_f32_e32 v8, v8
	v_exp_f32_e32 v9, v9
	v_add_f32_e32 v8, 1.0, v8
	v_add_f32_e32 v9, 1.0, v9
	v_rcp_f32_e32 v8, v8
	v_rcp_f32_e32 v9, v9
	s_nop 0
	v_pk_mul_f32 v[2:3], v[2:3], v[8:9]
	s_nop 0
	v_pk_mul_f32 v[8:9], v[4:5], v[2:3]
	v_cvt_pk_bf16_f32 v2, v10, v11
	v_cvt_pk_bf16_f32 v3, v12, v13
	v_cvt_pk_bf16_f32 v4, v6, v7
	v_cvt_pk_bf16_f32 v5, v8, v9
	global_store_dwordx4 v[14:15], v[2:5], off nt
	s_cbranch_vccnz .LBB0_365
	s_andn2_b64 vcc, exec, s[4:5]
	s_cbranch_vccnz .LBB0_364
	s_barrier
	s_branch .LBB0_364

; __device__ __forceinline__ unsigned pk2(float lo, float hi) { f32x2 v = {lo, hi}; bf16x2_t b = __builtin_convertvector(v, bf16x2_t); return __builtin_bit_cast(unsigned, b); }
;     __device__ __forceinline__ void operator()(const f32x4 (&acc)[2][2][4][2], const Unit& u, int wr, int wc, int fr, int fq, LAS unsigned char* lds, int tid) const {
;     ...
;             for (int m = 0; m < 4; ++m) { const size_t row = (size_t)(row0 + ai * HALF + m * 16); const float rs = rsv[ai][m]; gbf16* rowp = O + row * ldc + col0;
; #pragma unroll
;                 for (int bj = 0; bj < 2; ++bj) { const f32x4 v0 = acc[ai][bj][m][0] * rs, v1 = acc[ai][bj][m][1] * rs;
;                     u32x4 w; w.x = pk2(v0[0], v0[1]); w.y = pk2(v0[2], v0[3]); w.z = pk2(v1[0], v1[1]); w.w = pk2(v1[2], v1[3]);
;                     *(gu32x4*)(rowp + bj * HALF) = w; } }
.Lk3_rs_hit:
	s_andn2_b64 vcc, exec, s[2:3]
	v_mul_f32_e32 v174, v159, v226
	v_mul_f32_e32 v172, v159, v236
	v_mul_f32_e32 v170, v159, v237
	v_mul_f32_e32 v168, v159, v244
	v_mul_f32_e32 v166, v159, v245
	v_mul_f32_e32 v164, v159, v246
	v_mul_f32_e32 v162, v159, v247
	v_mul_f32_e32 v130, v159, v248
	v_mov_b64_e32 v[132:133], s[96:97]
	v_mad_i64_i32 v[160:161], s[20:21], v160, s33, v[132:133]
	v_ashrrev_i32_e32 v159, 31, v158
	v_lshlrev_b64 v[158:159], 1, v[158:159]
	v_pk_mul_f32 v[128:129], v[128:129], v[174:175] op_sel_hi:[1,0]
	v_pk_mul_f32 v[126:127], v[126:127], v[174:175] op_sel_hi:[1,0]
	v_pk_mul_f32 v[176:177], v[124:125], v[174:175] op_sel_hi:[1,0]
	v_pk_mul_f32 v[124:125], v[122:123], v[174:175] op_sel_hi:[1,0]
	v_lshl_add_u64 v[160:161], v[160:161], 0, v[158:159]
	v_cvt_pk_bf16_f32 v122, v126, v127
	v_cvt_pk_bf16_f32 v123, v128, v129
	v_cvt_pk_bf16_f32 v124, v124, v125
	v_cvt_pk_bf16_f32 v125, v176, v177
	global_store_dwordx4 v[160:161], v[122:125], off nt
	v_pk_mul_f32 v[116:117], v[116:117], v[174:175] op_sel_hi:[1,0]
	v_pk_mul_f32 v[114:115], v[114:115], v[174:175] op_sel_hi:[1,0]
	v_pk_mul_f32 v[122:123], v[108:109], v[174:175] op_sel_hi:[1,0]
	v_pk_mul_f32 v[108:109], v[106:107], v[174:175] op_sel_hi:[1,0]
	v_cvt_pk_bf16_f32 v106, v114, v115
	v_cvt_pk_bf16_f32 v107, v116, v117
	v_cvt_pk_bf16_f32 v108, v108, v109
	v_cvt_pk_bf16_f32 v109, v122, v123
	global_store_dwordx4 v[160:161], v[106:109], off offset:256 nt
	v_pk_mul_f32 v[112:113], v[112:113], v[172:173] op_sel_hi:[1,0]
	v_pk_mul_f32 v[110:111], v[110:111], v[172:173] op_sel_hi:[1,0]
	v_mad_i64_i32 v[106:107], s[20:21], v156, s33, v[132:133]
	v_lshl_add_u64 v[114:115], v[106:107], 0, v[158:159]
	v_pk_mul_f32 v[108:109], v[120:121], v[172:173] op_sel_hi:[1,0]
	v_pk_mul_f32 v[106:107], v[118:119], v[172:173] op_sel_hi:[1,0]
	v_pk_mul_f32 v[100:101], v[100:101], v[172:173] op_sel_hi:[1,0]
	v_cvt_pk_bf16_f32 v106, v106, v107
	v_cvt_pk_bf16_f32 v107, v108, v109
	v_cvt_pk_bf16_f32 v108, v110, v111
	v_cvt_pk_bf16_f32 v109, v112, v113
	global_store_dwordx4 v[114:115], v[106:109], off nt
	v_pk_mul_f32 v[98:99], v[98:99], v[172:173] op_sel_hi:[1,0]
	v_pk_mul_f32 v[96:97], v[96:97], v[170:171] op_sel_hi:[1,0]
	v_pk_mul_f32 v[106:107], v[92:93], v[172:173] op_sel_hi:[1,0]
	v_pk_mul_f32 v[92:93], v[90:91], v[172:173] op_sel_hi:[1,0]
	v_cvt_pk_bf16_f32 v90, v98, v99
	v_cvt_pk_bf16_f32 v91, v100, v101
	v_cvt_pk_bf16_f32 v92, v92, v93
	v_cvt_pk_bf16_f32 v93, v106, v107
	global_store_dwordx4 v[114:115], v[90:93], off offset:256 nt
	v_pk_mul_f32 v[94:95], v[94:95], v[170:171] op_sel_hi:[1,0]
	v_pk_mul_f32 v[84:85], v[84:85], v[170:171] op_sel_hi:[1,0]
	v_mad_i64_i32 v[90:91], s[20:21], v154, s33, v[132:133]
	v_lshl_add_u64 v[98:99], v[90:91], 0, v[158:159]
	v_pk_mul_f32 v[92:93], v[104:105], v[170:171] op_sel_hi:[1,0]
	v_pk_mul_f32 v[90:91], v[102:103], v[170:171] op_sel_hi:[1,0]
	v_pk_mul_f32 v[82:83], v[82:83], v[170:171] op_sel_hi:[1,0]
	v_cvt_pk_bf16_f32 v90, v90, v91
	v_cvt_pk_bf16_f32 v91, v92, v93
	v_cvt_pk_bf16_f32 v92, v94, v95
	v_cvt_pk_bf16_f32 v93, v96, v97
	global_store_dwordx4 v[98:99], v[90:93], off nt
	v_pk_mul_f32 v[80:81], v[80:81], v[168:169] op_sel_hi:[1,0]
	v_pk_mul_f32 v[78:79], v[78:79], v[168:169] op_sel_hi:[1,0]
	v_pk_mul_f32 v[90:91], v[76:77], v[170:171] op_sel_hi:[1,0]
	v_pk_mul_f32 v[76:77], v[74:75], v[170:171] op_sel_hi:[1,0]
	v_cvt_pk_bf16_f32 v74, v82, v83
	v_cvt_pk_bf16_f32 v75, v84, v85
	v_cvt_pk_bf16_f32 v76, v76, v77
	v_cvt_pk_bf16_f32 v77, v90, v91
	global_store_dwordx4 v[98:99], v[74:77], off offset:256 nt
	v_pk_mul_f32 v[72:73], v[72:73], v[168:169] op_sel_hi:[1,0]
	v_pk_mul_f32 v[70:71], v[70:71], v[168:169] op_sel_hi:[1,0]
	v_mad_i64_i32 v[74:75], s[20:21], v152, s33, v[132:133]
	v_lshl_add_u64 v[82:83], v[74:75], 0, v[158:159]
	v_pk_mul_f32 v[76:77], v[88:89], v[168:169] op_sel_hi:[1,0]
	v_pk_mul_f32 v[74:75], v[86:87], v[168:169] op_sel_hi:[1,0]
	v_pk_mul_f32 v[64:65], v[64:65], v[166:167] op_sel_hi:[1,0]
	v_cvt_pk_bf16_f32 v74, v74, v75
	v_cvt_pk_bf16_f32 v75, v76, v77
	v_cvt_pk_bf16_f32 v76, v78, v79
	v_cvt_pk_bf16_f32 v77, v80, v81
	global_store_dwordx4 v[82:83], v[74:77], off nt
	v_pk_mul_f32 v[62:63], v[62:63], v[166:167] op_sel_hi:[1,0]
; __device__ __forceinline__ unsigned pk2(float lo, float hi) { f32x2 v = {lo, hi}; bf16x2_t b = __builtin_convertvector(v, bf16x2_t); return __builtin_bit_cast(unsigned, b); }
; #define PG8_BAR __builtin_amdgcn_s_barrier()
;     __device__ __forceinline__ void operator()(const f32x4 (&acc)[2][2][4][2], const Unit& u, int wr, int wc, int fr, int fq, LAS unsigned char* lds, int tid) const {
;     ...
;             for (int m = 0; m < 4; ++m) { const size_t row = (size_t)(row0 + ai * HALF + m * 16); const float rs = rsv[ai][m]; gbf16* rowp = O + row * ldc + col0;
; #pragma unroll
;                 for (int bj = 0; bj < 2; ++bj) { const f32x4 v0 = acc[ai][bj][m][0] * rs, v1 = acc[ai][bj][m][1] * rs;
;                     u32x4 w; w.x = pk2(v0[0], v0[1]); w.y = pk2(v0[2], v0[3]); w.z = pk2(v1[0], v1[1]); w.w = pk2(v1[2], v1[3]);
;                     *(gu32x4*)(rowp + bj * HALF) = w; } }
; template <class Epi, class Sched>
; __device__ __forceinline__ void gemm_phase(LAS unsigned char* lds, const int tid, const Gemm g, const Sched& S, const Epi& E) {
;     ...
;         if (wr == 1) PG8_BAR;
	v_pk_mul_f32 v[52:53], v[52:53], v[166:167] op_sel_hi:[1,0]
	v_pk_mul_f32 v[74:75], v[68:69], v[168:169] op_sel_hi:[1,0]
	v_pk_mul_f32 v[68:69], v[66:67], v[168:169] op_sel_hi:[1,0]
	v_cvt_pk_bf16_f32 v66, v70, v71
	v_cvt_pk_bf16_f32 v67, v72, v73
	v_cvt_pk_bf16_f32 v68, v68, v69
	v_cvt_pk_bf16_f32 v69, v74, v75
	global_store_dwordx4 v[82:83], v[66:69], off offset:256 nt
	v_pk_mul_f32 v[50:51], v[50:51], v[166:167] op_sel_hi:[1,0]
	v_pk_mul_f32 v[48:49], v[48:49], v[164:165] op_sel_hi:[1,0]
	v_mad_i64_i32 v[66:67], s[20:21], v150, s33, v[132:133]
	v_pk_mul_f32 v[68:69], v[60:61], v[166:167] op_sel_hi:[1,0]
	v_pk_mul_f32 v[60:61], v[58:59], v[166:167] op_sel_hi:[1,0]
	v_lshl_add_u64 v[66:67], v[66:67], 0, v[158:159]
	v_cvt_pk_bf16_f32 v58, v62, v63
	v_cvt_pk_bf16_f32 v59, v64, v65
	v_cvt_pk_bf16_f32 v60, v60, v61
	v_cvt_pk_bf16_f32 v61, v68, v69
	global_store_dwordx4 v[66:67], v[58:61], off nt
	v_pk_mul_f32 v[46:47], v[46:47], v[164:165] op_sel_hi:[1,0]
	v_pk_mul_f32 v[36:37], v[36:37], v[164:165] op_sel_hi:[1,0]
	v_pk_mul_f32 v[58:59], v[44:45], v[166:167] op_sel_hi:[1,0]
	v_pk_mul_f32 v[44:45], v[42:43], v[166:167] op_sel_hi:[1,0]
	v_cvt_pk_bf16_f32 v42, v50, v51
	v_cvt_pk_bf16_f32 v43, v52, v53
	v_cvt_pk_bf16_f32 v44, v44, v45
	v_cvt_pk_bf16_f32 v45, v58, v59
	global_store_dwordx4 v[66:67], v[42:45], off offset:256 nt
	v_pk_mul_f32 v[34:35], v[34:35], v[164:165] op_sel_hi:[1,0]
	v_pk_mul_f32 v[32:33], v[32:33], v[162:163] op_sel_hi:[1,0]
	v_mad_i64_i32 v[42:43], s[20:21], v148, s33, v[132:133]
	v_lshl_add_u64 v[50:51], v[42:43], 0, v[158:159]
	v_pk_mul_f32 v[44:45], v[56:57], v[164:165] op_sel_hi:[1,0]
	v_pk_mul_f32 v[42:43], v[54:55], v[164:165] op_sel_hi:[1,0]
	v_pk_mul_f32 v[30:31], v[30:31], v[162:163] op_sel_hi:[1,0]
	v_cvt_pk_bf16_f32 v42, v42, v43
	v_cvt_pk_bf16_f32 v43, v44, v45
	v_cvt_pk_bf16_f32 v44, v46, v47
	v_cvt_pk_bf16_f32 v45, v48, v49
	global_store_dwordx4 v[50:51], v[42:45], off nt
	v_pk_mul_f32 v[20:21], v[20:21], v[162:163] op_sel_hi:[1,0]
	v_pk_mul_f32 v[18:19], v[18:19], v[162:163] op_sel_hi:[1,0]
	v_pk_mul_f32 v[42:43], v[28:29], v[164:165] op_sel_hi:[1,0]
	v_pk_mul_f32 v[28:29], v[26:27], v[164:165] op_sel_hi:[1,0]
	v_cvt_pk_bf16_f32 v26, v34, v35
	v_cvt_pk_bf16_f32 v27, v36, v37
	v_cvt_pk_bf16_f32 v28, v28, v29
	v_cvt_pk_bf16_f32 v29, v42, v43
	global_store_dwordx4 v[50:51], v[26:29], off offset:256 nt
	v_pk_mul_f32 v[16:17], v[16:17], v[130:131] op_sel_hi:[1,0]
	v_pk_mul_f32 v[14:15], v[14:15], v[130:131] op_sel_hi:[1,0]
	v_mad_i64_i32 v[26:27], s[20:21], v146, s33, v[132:133]
	v_lshl_add_u64 v[34:35], v[26:27], 0, v[158:159]
	v_pk_mul_f32 v[28:29], v[40:41], v[162:163] op_sel_hi:[1,0]
	v_pk_mul_f32 v[26:27], v[38:39], v[162:163] op_sel_hi:[1,0]
	v_pk_mul_f32 v[8:9], v[8:9], v[130:131] op_sel_hi:[1,0]
	v_cvt_pk_bf16_f32 v26, v26, v27
	v_cvt_pk_bf16_f32 v27, v28, v29
	v_cvt_pk_bf16_f32 v28, v30, v31
	v_cvt_pk_bf16_f32 v29, v32, v33
	global_store_dwordx4 v[34:35], v[26:29], off nt
	v_pk_mul_f32 v[6:7], v[6:7], v[130:131] op_sel_hi:[1,0]
	s_nop 0
	v_pk_mul_f32 v[26:27], v[12:13], v[162:163] op_sel_hi:[1,0]
	v_pk_mul_f32 v[12:13], v[10:11], v[162:163] op_sel_hi:[1,0]
	v_cvt_pk_bf16_f32 v10, v18, v19
	v_cvt_pk_bf16_f32 v11, v20, v21
	v_cvt_pk_bf16_f32 v12, v12, v13
	v_cvt_pk_bf16_f32 v13, v26, v27
	global_store_dwordx4 v[34:35], v[10:13], off offset:256 nt
	s_nop 1
	v_mad_i64_i32 v[10:11], s[20:21], v144, s33, v[132:133]
	v_lshl_add_u64 v[18:19], v[10:11], 0, v[158:159]
	v_pk_mul_f32 v[12:13], v[24:25], v[130:131] op_sel_hi:[1,0]
	v_pk_mul_f32 v[10:11], v[22:23], v[130:131] op_sel_hi:[1,0]
	s_mov_b64 s[20:21], -1
	v_cvt_pk_bf16_f32 v10, v10, v11
	v_cvt_pk_bf16_f32 v11, v12, v13
	v_cvt_pk_bf16_f32 v12, v14, v15
	v_cvt_pk_bf16_f32 v13, v16, v17
	global_store_dwordx4 v[18:19], v[10:13], off nt
	s_nop 1
	v_pk_mul_f32 v[10:11], v[4:5], v[130:131] op_sel_hi:[1,0]
	v_pk_mul_f32 v[4:5], v[2:3], v[130:131] op_sel_hi:[1,0]
	v_cvt_pk_bf16_f32 v2, v6, v7
	v_cvt_pk_bf16_f32 v3, v8, v9
	v_cvt_pk_bf16_f32 v4, v4, v5
	v_cvt_pk_bf16_f32 v5, v10, v11
	global_store_dwordx4 v[18:19], v[2:5], off offset:256 nt
	s_cbranch_vccnz .LBB0_555
	s_andn2_b64 vcc, exec, s[0:1]
	s_cbranch_vccnz .LBB0_554
	s_barrier
	s_branch .LBB0_554

; __device__ __forceinline__ unsigned pk2(float lo, float hi) { f32x2 v = {lo, hi}; bf16x2_t b = __builtin_convertvector(v, bf16x2_t); return __builtin_bit_cast(unsigned, b); }
; __device__ __forceinline__ float bflo(unsigned w) { return __uint_as_float(w << 16); }
; __device__ __forceinline__ float bfhi(unsigned w) { return __uint_as_float(w & 0xffff0000u); }
;     __device__ __forceinline__ void operator()(const f32x4 (&acc)[2][2][4][2], const Unit& u, int wr, int wc, int fr, int fq, LAS unsigned char* lds, int tid) const {
;     ...
;             for (int m = 0; m < 4; ++m) { const size_t off = (size_t)(row0 + ai * HALF + m * 16) * DM + col0;
; #pragma unroll
;                 for (int bj = 0; bj < 2; ++bj) {
;                     if (RES_BF16) rw[m][bj] = *(const gu32x4*)(resb + off + bj * HALF);
;                     else { rv[m][bj][0] = *(const gf32x4*)(resf + off + bj * HALF); rv[m][bj][1] = *(const gf32x4*)(resf + off + bj * HALF + 4); } } }
;             asm volatile("" ::: "memory");
;             if (RES_BF16) {
; #pragma unroll
;                 for (int m = 0; m < 4; ++m)
; #pragma unroll
;                     for (int bj = 0; bj < 2; ++bj) { const u32x4 w = rw[m][bj];
;                         rv[m][bj][0] = (f32x4){bflo(w.x), bfhi(w.x), bflo(w.y), bfhi(w.y)}; rv[m][bj][1] = (f32x4){bflo(w.z), bfhi(w.z), bflo(w.w), bfhi(w.w)}; } }
; #pragma unroll
;             for (int m = 0; m < 4; ++m) { const size_t off = (size_t)(row0 + ai * HALF + m * 16) * DM + col0; float ss = 0.f;
; #pragma unroll
;                 for (int bj = 0; bj < 2; ++bj) { const f32x4 v0 = rv[m][bj][0] + acc[ai][bj][m][0] * scale, v1 = rv[m][bj][1] + acc[ai][bj][m][1] * scale;
;                     u32x4 w; w.x = pk2(v0[0], v0[1]); w.y = pk2(v0[2], v0[3]); w.z = pk2(v1[0], v1[1]); w.w = pk2(v1[2], v1[3]);
;                     *(gu32x4*)(xb + off + bj * HALF) = w;
;                     ss += ((v0[0] * v0[0] + v0[1] * v0[1]) + (v0[2] * v0[2] + v0[3] * v0[3])) + ((v1[0] * v1[0] + v1[1] * v1[1]) + (v1[2] * v1[2] + v1[3] * v1[3])); }
;                 ss += __shfl_xor(ss, 16); ss += __shfl_xor(ss, 32);
;                 if (fq == 0) red[wc * 256 + ai * HALF + wr * 64 + m * 16 + fr] = ss; }
.LBB0_601:
	s_lshl_b32 s1, s1, 8
	v_add_u32_e32 v192, s1, v209
	v_lshl_or_b32 v188, s0, 8, v211
	v_ashrrev_i32_e32 v189, 31, v188
	v_ashrrev_i32_e32 v193, 31, v192
	v_lshl_add_u64 v[190:191], v[188:189], 2, s[56:57]
	v_lshlrev_b64 v[130:131], 12, v[192:193]
	v_lshl_add_u64 v[130:131], v[190:191], 0, v[130:131]
	global_load_dwordx4 v[216:219], v[130:131], off nt
	global_load_dwordx4 v[220:223], v[130:131], off offset:16 nt
	global_load_dwordx4 v[224:227], v[130:131], off offset:512 nt
	global_load_dwordx4 v[242:245], v[130:131], off offset:528 nt
	v_or_b32_e32 v206, 16, v192
	v_or_b32_e32 v204, 32, v192
	v_or_b32_e32 v194, 48, v192
	v_ashrrev_i32_e32 v207, 31, v206
	v_ashrrev_i32_e32 v205, 31, v204
	v_ashrrev_i32_e32 v195, 31, v194
	v_lshlrev_b64 v[130:131], 12, v[206:207]
	v_lshlrev_b64 v[132:133], 12, v[204:205]
	v_lshlrev_b64 v[134:135], 12, v[194:195]
	v_lshl_add_u64 v[130:131], v[190:191], 0, v[130:131]
	v_lshl_add_u64 v[132:133], v[190:191], 0, v[132:133]
	v_lshl_add_u64 v[134:135], v[190:191], 0, v[134:135]
	global_load_dwordx4 v[170:173], v[130:131], off offset:16 nt
	global_load_dwordx4 v[174:177], v[130:131], off nt
	global_load_dwordx4 v[162:165], v[130:131], off offset:528 nt
	global_load_dwordx4 v[166:169], v[130:131], off offset:512 nt
	global_load_dwordx4 v[154:157], v[132:133], off offset:16 nt
	global_load_dwordx4 v[158:161], v[132:133], off nt
	global_load_dwordx4 v[146:149], v[132:133], off offset:528 nt
	global_load_dwordx4 v[150:153], v[132:133], off offset:512 nt
	global_load_dwordx4 v[138:141], v[134:135], off offset:16 nt
	global_load_dwordx4 v[142:145], v[134:135], off nt
	s_nop 0
	global_load_dwordx4 v[130:133], v[134:135], off offset:528 nt
	s_nop 0
	global_load_dwordx4 v[134:137], v[134:135], off offset:512 nt
	v_lshlrev_b64 v[246:247], 11, v[192:193]
	s_waitcnt vmcnt(0)
	v_pk_fma_f32 v[128:129], v[128:129], 0.5, v[218:219] op_sel_hi:[1,0,1]
	v_pk_fma_f32 v[126:127], v[126:127], 0.5, v[216:217] op_sel_hi:[1,0,1]
	v_pk_fma_f32 v[124:125], v[124:125], 0.5, v[222:223] op_sel_hi:[1,0,1]
	v_pk_fma_f32 v[122:123], v[122:123], 0.5, v[220:221] op_sel_hi:[1,0,1]
	v_pk_fma_f32 v[120:121], v[120:121], 0.5, v[226:227] op_sel_hi:[1,0,1]
	v_pk_fma_f32 v[118:119], v[118:119], 0.5, v[224:225] op_sel_hi:[1,0,1]
	v_pk_fma_f32 v[216:217], v[116:117], 0.5, v[244:245] op_sel_hi:[1,0,1]
	v_pk_fma_f32 v[218:219], v[114:115], 0.5, v[242:243] op_sel_hi:[1,0,1]
	v_cvt_pk_bf16_f32 v114, v126, v127
	v_cvt_pk_bf16_f32 v115, v128, v129
	v_cvt_pk_bf16_f32 v116, v122, v123
	v_cvt_pk_bf16_f32 v117, v124, v125
	v_mul_f32_e32 v127, v127, v127
	v_mul_f32_e32 v129, v129, v129
	v_mul_f32_e32 v123, v123, v123
	v_mul_f32_e32 v125, v125, v125
	v_mul_f32_e32 v193, v119, v119
	v_mul_f32_e32 v200, v121, v121
	v_mul_f32_e32 v201, v219, v219
	v_mul_f32_e32 v215, v217, v217
	v_fmac_f32_e32 v127, v126, v126
	v_fmac_f32_e32 v129, v128, v128
	v_fmac_f32_e32 v123, v122, v122
	v_fmac_f32_e32 v125, v124, v124
	v_fmac_f32_e32 v193, v118, v118
	v_fmac_f32_e32 v200, v120, v120
	v_fmac_f32_e32 v201, v218, v218
	v_fmac_f32_e32 v215, v216, v216
	v_add_f32_e32 v122, v127, v129
	v_add_f32_e32 v123, v123, v125
	v_add_f32_e32 v124, v193, v200
	v_add_f32_e32 v125, v201, v215
	v_add_f32_e32 v122, v122, v123
	v_add_f32_e32 v123, v124, v125
	v_add_f32_e32 v124, v122, v123
	ds_bpermute_b32 v125, v229, v124
	v_lshl_add_u64 v[122:123], s[86:87], 0, v[246:247]
	v_lshl_add_u64 v[122:123], v[188:189], 1, v[122:123]
	global_store_dwordx4 v[122:123], v[114:117], off
	s_waitcnt lgkmcnt(0)
	s_nop 0
	v_add_f32_e32 v114, v124, v125
	ds_bpermute_b32 v115, v230, v114
	v_cvt_pk_bf16_f32 v116, v118, v119
	v_cvt_pk_bf16_f32 v117, v120, v121
	v_cvt_pk_bf16_f32 v118, v218, v219
	v_cvt_pk_bf16_f32 v119, v216, v217
	global_store_dwordx4 v[122:123], v[116:119], off offset:256
	s_and_saveexec_b64 s[20:21], s[2:3]
	s_cbranch_execz .LBB0_603
	s_waitcnt lgkmcnt(0)
	v_add_f32_e32 v114, v114, v115
	ds_write_b32 v212, v114

; __device__ __forceinline__ unsigned pk2(float lo, float hi) { f32x2 v = {lo, hi}; bf16x2_t b = __builtin_convertvector(v, bf16x2_t); return __builtin_bit_cast(unsigned, b); }
; __device__ __forceinline__ float bflo(unsigned w) { return __uint_as_float(w << 16); }
; __device__ __forceinline__ float bfhi(unsigned w) { return __uint_as_float(w & 0xffff0000u); }
;     __device__ __forceinline__ void operator()(const f32x4 (&acc)[2][2][4][2], const Unit& u, int wr, int wc, int fr, int fq, LAS unsigned char* lds, int tid) const {
;     ...
;             for (int m = 0; m < 4; ++m) { const size_t off = (size_t)(row0 + ai * HALF + m * 16) * DM + col0;
; #pragma unroll
;                 for (int bj = 0; bj < 2; ++bj) {
;                     if (RES_BF16) rw[m][bj] = *(const gu32x4*)(resb + off + bj * HALF);
;                     else { rv[m][bj][0] = *(const gf32x4*)(resf + off + bj * HALF); rv[m][bj][1] = *(const gf32x4*)(resf + off + bj * HALF + 4); } } }
;             asm volatile("" ::: "memory");
;             if (RES_BF16) {
; #pragma unroll
;                 for (int m = 0; m < 4; ++m)
; #pragma unroll
;                     for (int bj = 0; bj < 2; ++bj) { const u32x4 w = rw[m][bj];
;                         rv[m][bj][0] = (f32x4){bflo(w.x), bfhi(w.x), bflo(w.y), bfhi(w.y)}; rv[m][bj][1] = (f32x4){bflo(w.z), bfhi(w.z), bflo(w.w), bfhi(w.w)}; } }
; #pragma unroll
;             for (int m = 0; m < 4; ++m) { const size_t off = (size_t)(row0 + ai * HALF + m * 16) * DM + col0; float ss = 0.f;
; #pragma unroll
;                 for (int bj = 0; bj < 2; ++bj) { const f32x4 v0 = rv[m][bj][0] + acc[ai][bj][m][0] * scale, v1 = rv[m][bj][1] + acc[ai][bj][m][1] * scale;
;                     u32x4 w; w.x = pk2(v0[0], v0[1]); w.y = pk2(v0[2], v0[3]); w.z = pk2(v1[0], v1[1]); w.w = pk2(v1[2], v1[3]);
;                     *(gu32x4*)(xb + off + bj * HALF) = w;
;                     ss += ((v0[0] * v0[0] + v0[1] * v0[1]) + (v0[2] * v0[2] + v0[3] * v0[3])) + ((v1[0] * v1[0] + v1[1] * v1[1]) + (v1[2] * v1[2] + v1[3] * v1[3])); }
;                 ss += __shfl_xor(ss, 16); ss += __shfl_xor(ss, 32);
;                 if (fq == 0) red[wc * 256 + ai * HALF + wr * 64 + m * 16 + fr] = ss; }
.LBB0_609:
	s_or_b64 exec, exec, s[20:21]
	v_add_u32_e32 v136, 0x80, v192
	v_ashrrev_i32_e32 v137, 31, v136
	s_waitcnt lgkmcnt(0)
	v_lshlrev_b64 v[66:67], 12, v[136:137]
	v_lshl_add_u64 v[66:67], v[190:191], 0, v[66:67]
	global_load_dwordx4 v[120:123], v[66:67], off nt
	global_load_dwordx4 v[124:127], v[66:67], off offset:16 nt
	global_load_dwordx4 v[128:131], v[66:67], off offset:512 nt
	global_load_dwordx4 v[132:135], v[66:67], off offset:528 nt
	v_add_u32_e32 v118, 0x90, v192
	v_add_u32_e32 v116, 0xa0, v192
	v_add_u32_e32 v114, 0xb0, v192
	v_ashrrev_i32_e32 v119, 31, v118
	v_ashrrev_i32_e32 v117, 31, v116
	v_ashrrev_i32_e32 v115, 31, v114
	v_lshlrev_b64 v[66:67], 12, v[118:119]
	v_lshlrev_b64 v[68:69], 12, v[116:117]
	v_lshlrev_b64 v[70:71], 12, v[114:115]
	v_lshl_add_u64 v[66:67], v[190:191], 0, v[66:67]
	v_lshl_add_u64 v[68:69], v[190:191], 0, v[68:69]
	v_lshl_add_u64 v[70:71], v[190:191], 0, v[70:71]
	global_load_dwordx4 v[106:109], v[66:67], off offset:16 nt
	global_load_dwordx4 v[110:113], v[66:67], off nt
	global_load_dwordx4 v[98:101], v[66:67], off offset:528 nt
	global_load_dwordx4 v[102:105], v[66:67], off offset:512 nt
	global_load_dwordx4 v[90:93], v[68:69], off offset:16 nt
	global_load_dwordx4 v[94:97], v[68:69], off nt
	global_load_dwordx4 v[82:85], v[68:69], off offset:528 nt
	global_load_dwordx4 v[86:89], v[68:69], off offset:512 nt
	global_load_dwordx4 v[74:77], v[70:71], off offset:16 nt
	global_load_dwordx4 v[78:81], v[70:71], off nt
	s_nop 0
	global_load_dwordx4 v[66:69], v[70:71], off offset:528 nt
	s_nop 0
	global_load_dwordx4 v[70:73], v[70:71], off offset:512 nt
	v_lshlrev_b64 v[136:137], 11, v[136:137]
	s_waitcnt vmcnt(15)
	v_pk_fma_f32 v[64:65], v[64:65], 0.5, v[122:123] op_sel_hi:[1,0,1]
	v_pk_fma_f32 v[62:63], v[62:63], 0.5, v[120:121] op_sel_hi:[1,0,1]
	s_waitcnt vmcnt(14)
	v_pk_fma_f32 v[60:61], v[60:61], 0.5, v[126:127] op_sel_hi:[1,0,1]
	v_pk_fma_f32 v[58:59], v[58:59], 0.5, v[124:125] op_sel_hi:[1,0,1]
	s_waitcnt vmcnt(13)
	v_pk_fma_f32 v[56:57], v[56:57], 0.5, v[130:131] op_sel_hi:[1,0,1]
	v_pk_fma_f32 v[54:55], v[54:55], 0.5, v[128:129] op_sel_hi:[1,0,1]
	s_waitcnt vmcnt(12)
	v_pk_fma_f32 v[120:121], v[52:53], 0.5, v[134:135] op_sel_hi:[1,0,1]
	v_pk_fma_f32 v[122:123], v[50:51], 0.5, v[132:133] op_sel_hi:[1,0,1]
	v_cvt_pk_bf16_f32 v50, v62, v63
	v_cvt_pk_bf16_f32 v51, v64, v65
	v_cvt_pk_bf16_f32 v52, v58, v59
	v_cvt_pk_bf16_f32 v53, v60, v61
	v_mul_f32_e32 v63, v63, v63
	v_mul_f32_e32 v65, v65, v65
	v_mul_f32_e32 v59, v59, v59
	v_mul_f32_e32 v61, v61, v61
	v_mul_f32_e32 v124, v55, v55
	v_mul_f32_e32 v125, v57, v57
	v_mul_f32_e32 v126, v123, v123
	v_mul_f32_e32 v127, v121, v121
	v_fmac_f32_e32 v63, v62, v62
	v_fmac_f32_e32 v65, v64, v64
	v_fmac_f32_e32 v59, v58, v58
	v_fmac_f32_e32 v61, v60, v60
	v_fmac_f32_e32 v124, v54, v54
	v_fmac_f32_e32 v125, v56, v56
	v_fmac_f32_e32 v126, v122, v122
	v_fmac_f32_e32 v127, v120, v120
	v_add_f32_e32 v58, v63, v65
	v_add_f32_e32 v59, v59, v61
	v_add_f32_e32 v60, v124, v125
	v_add_f32_e32 v61, v126, v127
	v_add_f32_e32 v58, v58, v59
	v_add_f32_e32 v59, v60, v61
	v_add_f32_e32 v60, v58, v59
	ds_bpermute_b32 v61, v229, v60
	v_lshl_add_u64 v[58:59], s[86:87], 0, v[136:137]
	v_lshl_add_u64 v[58:59], v[188:189], 1, v[58:59]
	global_store_dwordx4 v[58:59], v[50:53], off
	s_waitcnt lgkmcnt(0)
	s_nop 0
	v_add_f32_e32 v50, v60, v61
	ds_bpermute_b32 v51, v230, v50
	v_cvt_pk_bf16_f32 v52, v54, v55
	v_cvt_pk_bf16_f32 v53, v56, v57
	v_cvt_pk_bf16_f32 v54, v122, v123
	v_cvt_pk_bf16_f32 v55, v120, v121
	global_store_dwordx4 v[58:59], v[52:55], off offset:256
	s_and_saveexec_b64 s[20:21], s[2:3]
	s_cbranch_execz .LBB0_611
	s_waitcnt lgkmcnt(0)
	v_add_f32_e32 v50, v50, v51
	ds_write_b32 v212, v50 offset:512

; __device__ __forceinline__ unsigned pk2(float lo, float hi) { f32x2 v = {lo, hi}; bf16x2_t b = __builtin_convertvector(v, bf16x2_t); return __builtin_bit_cast(unsigned, b); }
; __device__ __forceinline__ float sigmoidf_(float x) { return __builtin_amdgcn_rcpf(1.0f + __builtin_amdgcn_exp2f(-x * LOG2E)); }
;     __device__ __forceinline__ void operator()(const f32x4 (&acc)[2][2][4][2], const Unit& u, int wr, int wc, int fr, int fq, LAS unsigned char* lds, int tid) const {
;     ...
;             for (int m = 0; m < 4; ++m) { gbf16* rowp = O + (size_t)(row0 + ai * HALF + m * 16) * FF + col0;
;                 float h[8];
; #pragma unroll
;                 for (int n = 0; n < 2; ++n)
; #pragma unroll
;                     for (int e = 0; e < 4; ++e) { const float g = acc[ai][0][m][n][e], uu = acc[ai][1][m][n][e]; h[n * 4 + e] = g * sigmoidf_(g) * uu; }
;                 u32x4 w; w.x = pk2(h[0], h[1]); w.y = pk2(h[2], h[3]); w.z = pk2(h[4], h[5]); w.w = pk2(h[6], h[7]);
;                 *(gu32x4*)rowp = w; }
.LBB0_650:
	v_mul_f32_e32 v140, 0xbfb8aa3b, v126
	v_exp_f32_e32 v140, v140
	v_mul_f32_e32 v141, 0xbfb8aa3b, v127
	v_exp_f32_e32 v141, v141
	v_mul_f32_e32 v147, 0xbfb8aa3b, v128
	v_add_f32_e32 v140, 1.0, v140
	v_rcp_f32_e32 v150, v140
	v_add_f32_e32 v140, 1.0, v141
	v_rcp_f32_e32 v151, v140
	v_exp_f32_e32 v147, v147
	v_lshl_or_b32 v148, s36, 7, v144
	v_lshl_add_u32 v146, s56, 8, v142
	v_pk_mul_f32 v[126:127], v[126:127], v[150:151]
	v_mul_f32_e32 v150, 0xbfb8aa3b, v129
	v_exp_f32_e32 v150, v150
	v_pk_mul_f32 v[118:119], v[126:127], v[118:119]
	v_add_f32_e32 v126, 1.0, v147
	v_mul_f32_e32 v147, 0xbfb8aa3b, v122
	v_add_f32_e32 v127, 1.0, v150
	v_rcp_f32_e32 v126, v126
	v_rcp_f32_e32 v127, v127
	v_exp_f32_e32 v147, v147
	v_mul_f32_e32 v150, 0xbfb8aa3b, v123
	v_exp_f32_e32 v150, v150
	v_pk_mul_f32 v[126:127], v[128:129], v[126:127]
	v_add_f32_e32 v128, 1.0, v147
	v_mul_f32_e32 v147, 0xbfb8aa3b, v124
	v_add_f32_e32 v129, 1.0, v150
	v_exp_f32_e32 v147, v147
	v_mul_f32_e32 v150, 0xbfb8aa3b, v125
	v_exp_f32_e32 v151, v150
	v_rcp_f32_e32 v128, v128
	v_add_f32_e32 v147, 1.0, v147
	v_rcp_f32_e32 v129, v129
	v_rcp_f32_e32 v150, v147
	v_add_f32_e32 v147, 1.0, v151
	v_rcp_f32_e32 v151, v147
	v_pk_mul_f32 v[122:123], v[122:123], v[128:129]
	v_pk_mul_f32 v[120:121], v[126:127], v[120:121]
	v_pk_mul_f32 v[122:123], v[122:123], v[114:115]
	v_pk_mul_f32 v[114:115], v[124:125], v[150:151]
	v_ashrrev_i32_e32 v149, 31, v148
	v_pk_mul_f32 v[124:125], v[114:115], v[116:117]
	v_cvt_pk_bf16_f32 v117, v120, v121
	v_mul_f32_e32 v120, 0xbfb8aa3b, v110
	v_mul_f32_e32 v121, 0xbfb8aa3b, v111
	v_exp_f32_e32 v120, v120
	v_exp_f32_e32 v121, v121
	v_mov_b64_e32 v[140:141], s[88:89]
	v_mad_i64_i32 v[152:153], s[20:21], v146, s79, v[140:141]
	v_lshlrev_b64 v[114:115], 1, v[148:149]
	v_lshl_add_u64 v[126:127], v[152:153], 0, v[114:115]
	v_cvt_pk_bf16_f32 v116, v118, v119
	v_cvt_pk_bf16_f32 v118, v122, v123
	v_cvt_pk_bf16_f32 v119, v124, v125
	global_store_dwordx4 v[126:127], v[116:119], off nt
	s_andn2_b64 vcc, exec, s[2:3]
	s_mov_b64 s[2:3], -1
	v_add_f32_e32 v116, 1.0, v120
	v_add_f32_e32 v117, 1.0, v121
	v_rcp_f32_e32 v116, v116
	v_rcp_f32_e32 v117, v117
	v_or_b32_e32 v118, 16, v146
	v_mad_i64_i32 v[118:119], s[20:21], v118, s79, v[140:141]
	v_pk_mul_f32 v[110:111], v[110:111], v[116:117]
	v_mul_f32_e32 v116, 0xbfb8aa3b, v112
	v_mul_f32_e32 v117, 0xbfb8aa3b, v113
	v_exp_f32_e32 v116, v116
	v_exp_f32_e32 v117, v117
	v_pk_mul_f32 v[102:103], v[110:111], v[102:103]
	v_add_f32_e32 v110, 1.0, v116
	v_add_f32_e32 v111, 1.0, v117
	v_mul_f32_e32 v116, 0xbfb8aa3b, v106
	v_mul_f32_e32 v117, 0xbfb8aa3b, v107
	v_rcp_f32_e32 v110, v110
	v_rcp_f32_e32 v111, v111
	v_exp_f32_e32 v116, v116
	v_exp_f32_e32 v117, v117
	v_pk_mul_f32 v[110:111], v[112:113], v[110:111]
	v_add_f32_e32 v112, 1.0, v116
	v_add_f32_e32 v113, 1.0, v117
	v_mul_f32_e32 v116, 0xbfb8aa3b, v108
	v_mul_f32_e32 v117, 0xbfb8aa3b, v109
	v_exp_f32_e32 v116, v116
	v_exp_f32_e32 v117, v117
	v_rcp_f32_e32 v112, v112
	v_rcp_f32_e32 v113, v113
	v_add_f32_e32 v116, 1.0, v116
	v_add_f32_e32 v117, 1.0, v117
	v_rcp_f32_e32 v116, v116
	v_rcp_f32_e32 v117, v117
	v_pk_mul_f32 v[106:107], v[106:107], v[112:113]
	v_pk_mul_f32 v[104:105], v[110:111], v[104:105]
	v_pk_mul_f32 v[106:107], v[106:107], v[98:99]
	v_pk_mul_f32 v[98:99], v[108:109], v[116:117]
	v_lshl_add_u64 v[110:111], v[118:119], 0, v[114:115]
	v_pk_mul_f32 v[108:109], v[98:99], v[100:101]
	v_cvt_pk_bf16_f32 v98, v102, v103
	v_mul_f32_e32 v102, 0xbfb8aa3b, v94
	v_mul_f32_e32 v103, 0xbfb8aa3b, v95
	v_exp_f32_e32 v102, v102
	v_exp_f32_e32 v103, v103
	v_cvt_pk_bf16_f32 v99, v104, v105
	v_cvt_pk_bf16_f32 v100, v106, v107
	v_cvt_pk_bf16_f32 v101, v108, v109
	global_store_dwordx4 v[110:111], v[98:101], off nt
	s_nop 1
	v_add_f32_e32 v98, 1.0, v102
	v_add_f32_e32 v99, 1.0, v103
	v_rcp_f32_e32 v98, v98
	v_rcp_f32_e32 v99, v99
	v_or_b32_e32 v100, 32, v146
	v_mad_i64_i32 v[100:101], s[20:21], v100, s79, v[140:141]
	v_pk_mul_f32 v[94:95], v[94:95], v[98:99]
	v_mul_f32_e32 v98, 0xbfb8aa3b, v96
	v_mul_f32_e32 v99, 0xbfb8aa3b, v97
	v_exp_f32_e32 v98, v98
	v_exp_f32_e32 v99, v99
	v_pk_mul_f32 v[86:87], v[94:95], v[86:87]
	v_add_f32_e32 v94, 1.0, v98
	v_add_f32_e32 v95, 1.0, v99
	v_mul_f32_e32 v98, 0xbfb8aa3b, v90
	v_mul_f32_e32 v99, 0xbfb8aa3b, v91
	v_rcp_f32_e32 v94, v94
	v_rcp_f32_e32 v95, v95
	v_exp_f32_e32 v98, v98
	v_exp_f32_e32 v99, v99
	v_pk_mul_f32 v[94:95], v[96:97], v[94:95]
	v_add_f32_e32 v96, 1.0, v98
	v_add_f32_e32 v97, 1.0, v99
	v_mul_f32_e32 v98, 0xbfb8aa3b, v92
	v_mul_f32_e32 v99, 0xbfb8aa3b, v93
	v_exp_f32_e32 v98, v98
	v_exp_f32_e32 v99, v99
	v_rcp_f32_e32 v96, v96
	v_rcp_f32_e32 v97, v97
	v_add_f32_e32 v98, 1.0, v98
	v_add_f32_e32 v99, 1.0, v99
	v_rcp_f32_e32 v98, v98
	v_rcp_f32_e32 v99, v99
	v_pk_mul_f32 v[90:91], v[90:91], v[96:97]
	v_pk_mul_f32 v[88:89], v[94:95], v[88:89]
	v_pk_mul_f32 v[90:91], v[90:91], v[82:83]
	v_pk_mul_f32 v[82:83], v[92:93], v[98:99]
	v_lshl_add_u64 v[94:95], v[100:101], 0, v[114:115]
	v_pk_mul_f32 v[92:93], v[82:83], v[84:85]
	v_cvt_pk_bf16_f32 v82, v86, v87
	v_mul_f32_e32 v86, 0xbfb8aa3b, v78
	v_mul_f32_e32 v87, 0xbfb8aa3b, v79
	v_exp_f32_e32 v86, v86
	v_exp_f32_e32 v87, v87
	v_cvt_pk_bf16_f32 v83, v88, v89
	v_cvt_pk_bf16_f32 v84, v90, v91
	v_cvt_pk_bf16_f32 v85, v92, v93
	global_store_dwordx4 v[94:95], v[82:85], off nt
	s_nop 1
	v_add_f32_e32 v82, 1.0, v86
	v_add_f32_e32 v83, 1.0, v87
	v_rcp_f32_e32 v82, v82
	v_rcp_f32_e32 v83, v83
	v_or_b32_e32 v84, 48, v146
	v_mad_i64_i32 v[84:85], s[20:21], v84, s79, v[140:141]
	v_pk_mul_f32 v[78:79], v[78:79], v[82:83]
	v_mul_f32_e32 v82, 0xbfb8aa3b, v80
	v_mul_f32_e32 v83, 0xbfb8aa3b, v81
	v_exp_f32_e32 v82, v82
; __device__ __forceinline__ unsigned pk2(float lo, float hi) { f32x2 v = {lo, hi}; bf16x2_t b = __builtin_convertvector(v, bf16x2_t); return __builtin_bit_cast(unsigned, b); }
; __device__ __forceinline__ float sigmoidf_(float x) { return __builtin_amdgcn_rcpf(1.0f + __builtin_amdgcn_exp2f(-x * LOG2E)); }
;     __device__ __forceinline__ void operator()(const f32x4 (&acc)[2][2][4][2], const Unit& u, int wr, int wc, int fr, int fq, LAS unsigned char* lds, int tid) const {
;     ...
;             for (int m = 0; m < 4; ++m) { gbf16* rowp = O + (size_t)(row0 + ai * HALF + m * 16) * FF + col0;
;                 float h[8];
; #pragma unroll
;                 for (int n = 0; n < 2; ++n)
; #pragma unroll
;                     for (int e = 0; e < 4; ++e) { const float g = acc[ai][0][m][n][e], uu = acc[ai][1][m][n][e]; h[n * 4 + e] = g * sigmoidf_(g) * uu; }
;                 u32x4 w; w.x = pk2(h[0], h[1]); w.y = pk2(h[2], h[3]); w.z = pk2(h[4], h[5]); w.w = pk2(h[6], h[7]);
;                 *(gu32x4*)rowp = w; }
	v_exp_f32_e32 v83, v83
	v_pk_mul_f32 v[70:71], v[78:79], v[70:71]
	v_add_f32_e32 v78, 1.0, v82
	v_add_f32_e32 v79, 1.0, v83
	v_mul_f32_e32 v82, 0xbfb8aa3b, v74
	v_mul_f32_e32 v83, 0xbfb8aa3b, v75
	v_rcp_f32_e32 v78, v78
	v_rcp_f32_e32 v79, v79
	v_exp_f32_e32 v82, v82
	v_exp_f32_e32 v83, v83
	v_pk_mul_f32 v[78:79], v[80:81], v[78:79]
	v_add_f32_e32 v80, 1.0, v82
	v_add_f32_e32 v81, 1.0, v83
	v_mul_f32_e32 v82, 0xbfb8aa3b, v76
	v_mul_f32_e32 v83, 0xbfb8aa3b, v77
	v_exp_f32_e32 v82, v82
	v_exp_f32_e32 v83, v83
	v_rcp_f32_e32 v80, v80
	v_rcp_f32_e32 v81, v81
	v_add_f32_e32 v82, 1.0, v82
	v_add_f32_e32 v83, 1.0, v83
	v_rcp_f32_e32 v82, v82
	v_rcp_f32_e32 v83, v83
	v_pk_mul_f32 v[74:75], v[74:75], v[80:81]
	v_pk_mul_f32 v[72:73], v[78:79], v[72:73]
	v_pk_mul_f32 v[74:75], v[74:75], v[66:67]
	v_pk_mul_f32 v[66:67], v[76:77], v[82:83]
	v_lshl_add_u64 v[78:79], v[84:85], 0, v[114:115]
	v_pk_mul_f32 v[76:77], v[66:67], v[68:69]
	v_cvt_pk_bf16_f32 v66, v70, v71
	v_mul_f32_e32 v70, 0xbfb8aa3b, v62
	v_mul_f32_e32 v71, 0xbfb8aa3b, v63
	v_exp_f32_e32 v70, v70
	v_exp_f32_e32 v71, v71
	v_cvt_pk_bf16_f32 v67, v72, v73
	v_cvt_pk_bf16_f32 v68, v74, v75
	v_cvt_pk_bf16_f32 v69, v76, v77
	global_store_dwordx4 v[78:79], v[66:69], off nt
	s_nop 1
	v_add_f32_e32 v66, 1.0, v70
	v_add_f32_e32 v67, 1.0, v71
	v_rcp_f32_e32 v66, v66
	v_rcp_f32_e32 v67, v67
	v_add_u32_e32 v68, 0x80, v146
	v_mad_i64_i32 v[68:69], s[20:21], v68, s79, v[140:141]
	v_pk_mul_f32 v[62:63], v[62:63], v[66:67]
	v_mul_f32_e32 v66, 0xbfb8aa3b, v64
	v_mul_f32_e32 v67, 0xbfb8aa3b, v65
	v_exp_f32_e32 v66, v66
	v_exp_f32_e32 v67, v67
	v_pk_mul_f32 v[54:55], v[62:63], v[54:55]
	v_add_f32_e32 v62, 1.0, v66
	v_add_f32_e32 v63, 1.0, v67
	v_mul_f32_e32 v66, 0xbfb8aa3b, v58
	v_mul_f32_e32 v67, 0xbfb8aa3b, v59
	v_rcp_f32_e32 v62, v62
	v_rcp_f32_e32 v63, v63
	v_exp_f32_e32 v66, v66
	v_exp_f32_e32 v67, v67
	v_pk_mul_f32 v[62:63], v[64:65], v[62:63]
	v_add_f32_e32 v64, 1.0, v66
	v_add_f32_e32 v65, 1.0, v67
	v_mul_f32_e32 v66, 0xbfb8aa3b, v60
	v_mul_f32_e32 v67, 0xbfb8aa3b, v61
	v_exp_f32_e32 v66, v66
	v_exp_f32_e32 v67, v67
	v_rcp_f32_e32 v64, v64
	v_rcp_f32_e32 v65, v65
	v_add_f32_e32 v66, 1.0, v66
	v_add_f32_e32 v67, 1.0, v67
	v_rcp_f32_e32 v66, v66
	v_rcp_f32_e32 v67, v67
	v_pk_mul_f32 v[58:59], v[58:59], v[64:65]
	v_pk_mul_f32 v[56:57], v[62:63], v[56:57]
	v_pk_mul_f32 v[58:59], v[58:59], v[50:51]
	v_pk_mul_f32 v[50:51], v[60:61], v[66:67]
	v_lshl_add_u64 v[62:63], v[68:69], 0, v[114:115]
	v_pk_mul_f32 v[60:61], v[50:51], v[52:53]
	v_cvt_pk_bf16_f32 v50, v54, v55
	v_mul_f32_e32 v54, 0xbfb8aa3b, v46
	v_mul_f32_e32 v55, 0xbfb8aa3b, v47
	v_exp_f32_e32 v54, v54
	v_exp_f32_e32 v55, v55
	v_cvt_pk_bf16_f32 v51, v56, v57
	v_cvt_pk_bf16_f32 v52, v58, v59
	v_cvt_pk_bf16_f32 v53, v60, v61
	global_store_dwordx4 v[62:63], v[50:53], off nt
	s_nop 1
	v_add_f32_e32 v50, 1.0, v54
	v_add_f32_e32 v51, 1.0, v55
	v_rcp_f32_e32 v50, v50
	v_rcp_f32_e32 v51, v51
	v_add_u32_e32 v52, 0x90, v146
	v_mad_i64_i32 v[52:53], s[20:21], v52, s79, v[140:141]
	v_pk_mul_f32 v[46:47], v[46:47], v[50:51]
	v_mul_f32_e32 v50, 0xbfb8aa3b, v48
	v_mul_f32_e32 v51, 0xbfb8aa3b, v49
	v_exp_f32_e32 v50, v50
	v_exp_f32_e32 v51, v51
	v_pk_mul_f32 v[38:39], v[46:47], v[38:39]
	v_add_f32_e32 v46, 1.0, v50
	v_add_f32_e32 v47, 1.0, v51
	v_mul_f32_e32 v50, 0xbfb8aa3b, v42
	v_mul_f32_e32 v51, 0xbfb8aa3b, v43
	v_rcp_f32_e32 v46, v46
	v_rcp_f32_e32 v47, v47
	v_exp_f32_e32 v50, v50
	v_exp_f32_e32 v51, v51
	v_pk_mul_f32 v[46:47], v[48:49], v[46:47]
	v_add_f32_e32 v48, 1.0, v50
	v_add_f32_e32 v49, 1.0, v51
	v_mul_f32_e32 v50, 0xbfb8aa3b, v44
	v_mul_f32_e32 v51, 0xbfb8aa3b, v45
	v_exp_f32_e32 v50, v50
	v_exp_f32_e32 v51, v51
	v_rcp_f32_e32 v48, v48
	v_rcp_f32_e32 v49, v49
	v_add_f32_e32 v50, 1.0, v50
; __device__ __forceinline__ unsigned pk2(float lo, float hi) { f32x2 v = {lo, hi}; bf16x2_t b = __builtin_convertvector(v, bf16x2_t); return __builtin_bit_cast(unsigned, b); }
; __device__ __forceinline__ float sigmoidf_(float x) { return __builtin_amdgcn_rcpf(1.0f + __builtin_amdgcn_exp2f(-x * LOG2E)); }
; #define PG8_BAR __builtin_amdgcn_s_barrier()
;     __device__ __forceinline__ void operator()(const f32x4 (&acc)[2][2][4][2], const Unit& u, int wr, int wc, int fr, int fq, LAS unsigned char* lds, int tid) const {
;     ...
;             for (int m = 0; m < 4; ++m) { gbf16* rowp = O + (size_t)(row0 + ai * HALF + m * 16) * FF + col0;
;                 float h[8];
; #pragma unroll
;                 for (int n = 0; n < 2; ++n)
; #pragma unroll
;                     for (int e = 0; e < 4; ++e) { const float g = acc[ai][0][m][n][e], uu = acc[ai][1][m][n][e]; h[n * 4 + e] = g * sigmoidf_(g) * uu; }
;                 u32x4 w; w.x = pk2(h[0], h[1]); w.y = pk2(h[2], h[3]); w.z = pk2(h[4], h[5]); w.w = pk2(h[6], h[7]);
;                 *(gu32x4*)rowp = w; }
; template <class Epi, class Sched>
; __device__ __forceinline__ void gemm_phase(LAS unsigned char* lds, const int tid, const Gemm g, const Sched& S, const Epi& E) {
;     ...
;         if (wr == 1) PG8_BAR;
	v_add_f32_e32 v51, 1.0, v51
	v_rcp_f32_e32 v50, v50
	v_rcp_f32_e32 v51, v51
	v_pk_mul_f32 v[42:43], v[42:43], v[48:49]
	v_pk_mul_f32 v[40:41], v[46:47], v[40:41]
	v_pk_mul_f32 v[42:43], v[42:43], v[34:35]
	v_pk_mul_f32 v[34:35], v[44:45], v[50:51]
	v_lshl_add_u64 v[46:47], v[52:53], 0, v[114:115]
	v_pk_mul_f32 v[44:45], v[34:35], v[36:37]
	v_cvt_pk_bf16_f32 v34, v38, v39
	v_mul_f32_e32 v38, 0xbfb8aa3b, v30
	v_mul_f32_e32 v39, 0xbfb8aa3b, v31
	v_exp_f32_e32 v38, v38
	v_exp_f32_e32 v39, v39
	v_cvt_pk_bf16_f32 v35, v40, v41
	v_cvt_pk_bf16_f32 v36, v42, v43
	v_cvt_pk_bf16_f32 v37, v44, v45
	global_store_dwordx4 v[46:47], v[34:37], off nt
	s_nop 1
	v_add_f32_e32 v34, 1.0, v38
	v_add_f32_e32 v35, 1.0, v39
	v_rcp_f32_e32 v34, v34
	v_rcp_f32_e32 v35, v35
	v_add_u32_e32 v36, 0xa0, v146
	v_mad_i64_i32 v[36:37], s[20:21], v36, s79, v[140:141]
	v_pk_mul_f32 v[30:31], v[30:31], v[34:35]
	v_mul_f32_e32 v34, 0xbfb8aa3b, v32
	v_mul_f32_e32 v35, 0xbfb8aa3b, v33
	v_exp_f32_e32 v34, v34
	v_exp_f32_e32 v35, v35
	v_pk_mul_f32 v[22:23], v[30:31], v[22:23]
	v_add_f32_e32 v30, 1.0, v34
	v_add_f32_e32 v31, 1.0, v35
	v_mul_f32_e32 v34, 0xbfb8aa3b, v26
	v_mul_f32_e32 v35, 0xbfb8aa3b, v27
	v_rcp_f32_e32 v30, v30
	v_rcp_f32_e32 v31, v31
	v_exp_f32_e32 v34, v34
	v_exp_f32_e32 v35, v35
	v_pk_mul_f32 v[30:31], v[32:33], v[30:31]
	v_add_f32_e32 v32, 1.0, v34
	v_add_f32_e32 v33, 1.0, v35
	v_mul_f32_e32 v34, 0xbfb8aa3b, v28
	v_mul_f32_e32 v35, 0xbfb8aa3b, v29
	v_exp_f32_e32 v34, v34
	v_exp_f32_e32 v35, v35
	v_rcp_f32_e32 v32, v32
	v_rcp_f32_e32 v33, v33
	v_add_f32_e32 v34, 1.0, v34
	v_add_f32_e32 v35, 1.0, v35
	v_rcp_f32_e32 v34, v34
	v_rcp_f32_e32 v35, v35
	v_pk_mul_f32 v[26:27], v[26:27], v[32:33]
	v_pk_mul_f32 v[24:25], v[30:31], v[24:25]
	v_pk_mul_f32 v[26:27], v[26:27], v[18:19]
	v_pk_mul_f32 v[18:19], v[28:29], v[34:35]
	v_lshl_add_u64 v[30:31], v[36:37], 0, v[114:115]
	v_pk_mul_f32 v[28:29], v[18:19], v[20:21]
	v_cvt_pk_bf16_f32 v18, v22, v23
	v_mul_f32_e32 v22, 0xbfb8aa3b, v14
	v_mul_f32_e32 v23, 0xbfb8aa3b, v15
	v_exp_f32_e32 v22, v22
	v_exp_f32_e32 v23, v23
	v_cvt_pk_bf16_f32 v19, v24, v25
	v_cvt_pk_bf16_f32 v20, v26, v27
	v_cvt_pk_bf16_f32 v21, v28, v29
	global_store_dwordx4 v[30:31], v[18:21], off nt
	s_nop 1
	v_add_f32_e32 v18, 1.0, v22
	v_add_f32_e32 v19, 1.0, v23
	v_rcp_f32_e32 v18, v18
	v_rcp_f32_e32 v19, v19
	v_add_u32_e32 v20, 0xb0, v146
	v_mad_i64_i32 v[20:21], s[20:21], v20, s79, v[140:141]
	v_pk_mul_f32 v[14:15], v[14:15], v[18:19]
	v_mul_f32_e32 v18, 0xbfb8aa3b, v16
	v_mul_f32_e32 v19, 0xbfb8aa3b, v17
	v_exp_f32_e32 v18, v18
	v_exp_f32_e32 v19, v19
	v_pk_mul_f32 v[6:7], v[14:15], v[6:7]
	v_add_f32_e32 v14, 1.0, v18
	v_add_f32_e32 v15, 1.0, v19
	v_mul_f32_e32 v18, 0xbfb8aa3b, v10
	v_mul_f32_e32 v19, 0xbfb8aa3b, v11
	v_rcp_f32_e32 v14, v14
	v_rcp_f32_e32 v15, v15
	v_exp_f32_e32 v18, v18
	v_exp_f32_e32 v19, v19
	v_pk_mul_f32 v[14:15], v[16:17], v[14:15]
	v_add_f32_e32 v16, 1.0, v18
	v_add_f32_e32 v17, 1.0, v19
	v_mul_f32_e32 v18, 0xbfb8aa3b, v12
	v_mul_f32_e32 v19, 0xbfb8aa3b, v13
	v_exp_f32_e32 v18, v18
	v_exp_f32_e32 v19, v19
	v_rcp_f32_e32 v16, v16
	v_rcp_f32_e32 v17, v17
	v_add_f32_e32 v18, 1.0, v18
	v_add_f32_e32 v19, 1.0, v19
	v_rcp_f32_e32 v18, v18
	v_rcp_f32_e32 v19, v19
	v_pk_mul_f32 v[10:11], v[10:11], v[16:17]
	v_pk_mul_f32 v[8:9], v[14:15], v[8:9]
	v_pk_mul_f32 v[10:11], v[10:11], v[2:3]
	v_pk_mul_f32 v[2:3], v[12:13], v[18:19]
	v_lshl_add_u64 v[14:15], v[20:21], 0, v[114:115]
	v_pk_mul_f32 v[12:13], v[2:3], v[4:5]
	v_cvt_pk_bf16_f32 v2, v6, v7
	v_cvt_pk_bf16_f32 v3, v8, v9
	v_cvt_pk_bf16_f32 v4, v10, v11
	v_cvt_pk_bf16_f32 v5, v12, v13
	global_store_dwordx4 v[14:15], v[2:5], off nt
	s_cbranch_vccnz .LBB0_643
	s_andn2_b64 vcc, exec, s[0:1]
	s_cbranch_vccnz .LBB0_642
	s_barrier
	s_branch .LBB0_642
